# EpiQ rope epilogue: next row's cos/sin table loads issued one row ahead (8 serialized load-wait-rotate-store rounds pipelined)
# speedup vs baseline: 1.0066x; 1.0066x over previous
.LBB0_847:
	v_mov_b32_e32 v145, v165
	v_and_b32_e32 v157, 64, v219
	v_lshrrev_b32_e32 v146, 31, v145
	v_add_u32_e32 v148, v145, v146
	v_and_b32_e32 v146, 0x3ffffffe, v148
	v_sub_u32_e32 v146, v145, v146
	v_lshlrev_b32_e32 v146, 2, v146
	v_ashrrev_i32_e32 v147, 31, v146
	v_lshl_add_u64 v[150:151], v[146:147], 2, s[18:19]
	v_xor_b32_e32 v146, 1, v219
	v_add_u32_e32 v147, 64, v157
	s_lshl_b32 s0, s34, 8
	v_cmp_lt_i32_e32 vcc, v146, v147
	s_add_i32 s0, s0, s52
	v_ashrrev_i32_e32 v156, 1, v148
	v_cndmask_b32_e32 v146, v219, v146, vcc
	v_lshlrev_b32_e32 v158, 2, v146
	v_and_b32_e32 v146, 0xffffff80, v148
	v_and_or_b32 v147, v156, 63, s0
	v_add_u32_e32 v152, v147, v146
	v_ashrrev_i32_e32 v153, 31, v152
	v_lshlrev_b64 v[146:147], 5, v[152:153]
	v_lshl_add_u64 v[146:147], v[150:151], 0, v[146:147]
	v_add_co_u32_e32 v178, vcc, 0x1000, v146
	v_addc_co_u32_e32 v179, vcc, 0, v147, vcc
	global_load_dwordx4 v[160:163], v[146:147], off offset:1024
	global_load_dwordx4 v[174:177], v[178:179], off
	global_load_dwordx4 v[194:197], v[178:179], off offset:1024
	global_load_dwordx4 v[146:149], v[146:147], off
	v_and_b32_e32 v145, 15, v145
	v_lshlrev_b32_e32 v145, 3, v145
	v_lshl_or_b32 v145, v157, 2, v145
	s_cmp_gt_i32 s62, 3
	v_or_b32_e32 v144, s0, v137
	s_cselect_b64 s[34:35], -1, 0
	s_mov_b64 s[16:17], -1
	v_lshlrev_b32_e32 v180, 1, v136
	s_waitcnt vmcnt(0)
	v_mov_b32_e32 v154, v147
	v_mov_b32_e32 v155, v148
	v_mov_b32_e32 v147, v149
	v_pk_add_f32 v[146:147], v[154:155], v[146:147]
	s_nop 0
	v_add_f32_e32 v146, v146, v147
	s_nop 1
	s_waitcnt lgkmcnt(0)
	v_add_f32_dpp v146, v146, v146 quad_perm:[1,0,3,2] row_mask:0xf bank_mask:0xf
	v_fmamk_f32 v146, v146, 0x3b2aaaab, v200
	v_rsq_f32_e32 v153, v146
	v_add_u32_e32 v146, 32, v156
	v_lshlrev_b32_e32 v147, 1, v146
	v_and_b32_e32 v147, 0xffffff80, v147
	v_and_or_b32 v146, v146, 63, s0
	v_add_u32_e32 v146, v146, v147
	v_ashrrev_i32_e32 v147, 31, v146
	v_lshlrev_b64 v[146:147], 5, v[146:147]
	v_lshl_add_u64 v[146:147], v[150:151], 0, v[146:147]
	ds_bpermute_b32 v173, v145, v153 offset:128
	s_waitcnt vmcnt(0)
	v_mov_b32_e32 v146, v160
	v_mov_b32_e32 v147, v161
	v_mov_b32_e32 v148, v162
	v_mov_b32_e32 v149, v163
	v_add_f32_e32 v146, v146, v147
	v_add_f32_e32 v147, v148, v149
	v_add_f32_e32 v146, v146, v147
	s_nop 1
	s_waitcnt lgkmcnt(0)
	v_add_f32_dpp v146, v146, v146 quad_perm:[1,0,3,2] row_mask:0xf bank_mask:0xf
	v_fmamk_f32 v146, v146, 0x3b2aaaab, v200
	v_rsq_f32_e32 v154, v146
	v_add_u32_e32 v146, 0x80, v152
	v_ashrrev_i32_e32 v147, 31, v146
	v_lshlrev_b64 v[146:147], 5, v[146:147]
	v_lshl_add_u64 v[146:147], v[150:151], 0, v[146:147]
	ds_bpermute_b32 v172, v145, v154
	ds_bpermute_b32 v171, v145, v154 offset:128
	s_waitcnt vmcnt(0)
	v_mov_b32_e32 v146, v174
	v_mov_b32_e32 v147, v175
	v_mov_b32_e32 v148, v176
	v_mov_b32_e32 v149, v177
	v_add_f32_e32 v146, v146, v147
	v_add_f32_e32 v147, v148, v149
	v_add_f32_e32 v146, v146, v147
	s_nop 1
	s_waitcnt lgkmcnt(0)
	v_add_f32_dpp v146, v146, v146 quad_perm:[1,0,3,2] row_mask:0xf bank_mask:0xf
	v_fmamk_f32 v146, v146, 0x3b2aaaab, v200
	v_rsq_f32_e32 v152, v146
	v_add_u32_e32 v146, 0x60, v156
	v_lshlrev_b32_e32 v147, 1, v146
	v_and_b32_e32 v147, 0xffffff80, v147
	v_and_or_b32 v146, v146, 63, s0
	v_add_u32_e32 v146, v146, v147
	v_ashrrev_i32_e32 v147, 31, v146
	v_lshlrev_b64 v[146:147], 5, v[146:147]
	v_lshl_add_u64 v[146:147], v[150:151], 0, v[146:147]
	ds_bpermute_b32 v170, v145, v152
	ds_bpermute_b32 v169, v145, v152 offset:128
	s_lshl_b32 s0, s62, 2
	s_add_i32 s0, s58, s0
	s_mulk_i32 s0, 0xc0
	s_ashr_i32 s1, s0, 31
	s_cmp_lt_i32 s62, 4
	s_waitcnt vmcnt(0)
	v_mov_b32_e32 v146, v194
	v_mov_b32_e32 v147, v195
	v_mov_b32_e32 v148, v196
	v_mov_b32_e32 v149, v197
	v_add_f32_e32 v146, v146, v147
	v_add_f32_e32 v147, v148, v149
	v_add_f32_e32 v146, v146, v147
	s_nop 1
	s_waitcnt lgkmcnt(0)
	v_add_f32_dpp v146, v146, v146 quad_perm:[1,0,3,2] row_mask:0xf bank_mask:0xf
	v_fmamk_f32 v146, v146, 0x3b2aaaab, v200
	v_rsq_f32_e32 v146, v146
	ds_bpermute_b32 v147, v145, v153
	ds_bpermute_b32 v168, v145, v146
	ds_bpermute_b32 v167, v145, v146 offset:128
	s_waitcnt lgkmcnt(2)
	v_mul_f32_e32 v146, 0x3dd53b94, v147
	v_mov_b32_e32 v147, v146
	v_pk_mul_f32 v[126:127], v[126:127], v[146:147] op_sel_hi:[1,0]
	v_pk_mul_f32 v[124:125], v[124:125], v[146:147] op_sel_hi:[1,0]
	v_ashrrev_i32_e32 v145, 31, v144
	v_pk_mul_f32 v[116:117], v[116:117], v[146:147]
	v_pk_mul_f32 v[120:121], v[120:121], v[146:147]
	v_pk_mul_f32 v[112:113], v[112:113], v[146:147]
	s_cbranch_scc1 .LBB0_849
	v_lshlrev_b64 v[148:149], 8, v[144:145]
	v_lshl_add_u64 v[152:153], v[138:139], 0, v[148:149]
	global_load_dwordx4 v[156:159], v[152:153], off offset:32
	global_load_dwordx4 v[174:177], v[152:153], off offset:48
	global_load_dwordx4 v[148:151], v[152:153], off
	global_load_dwordx4 v[160:163], v[152:153], off offset:16
	v_mov_b32_e32 v147, v146
	v_pk_mul_f32 v[178:179], v[118:119], v[146:147]
	s_mov_b64 s[16:17], 0
	s_waitcnt vmcnt(3)
	v_mov_b32_e32 v198, v157
	v_mov_b32_e32 v199, v159
	s_waitcnt vmcnt(1)
	v_mov_b32_e32 v196, v149
	s_waitcnt vmcnt(0)
	v_or_b32_e32 v202, 16, v144
	v_ashrrev_i32_e32 v203, 31, v202
	v_lshlrev_b64 v[202:203], 8, v[202:203]
	v_lshl_add_u64 v[202:203], v[138:139], 0, v[202:203]
	global_load_dwordx4 v[206:209], v[202:203], off offset:32
	global_load_dwordx4 v[210:213], v[202:203], off offset:48
	global_load_dwordx4 v[214:217], v[202:203], off
	global_load_dwordx4 v[220:223], v[202:203], off offset:16
	v_mov_b32_e32 v194, v161
	v_mov_b32_e32 v195, v163
	v_pk_mul_f32 v[152:153], v[178:179], v[194:195]
	v_mov_b32_e32 v197, v151
	v_mov_b32_e32 v161, v162
	v_mov_b32_e32 v149, v150
	v_pk_mul_f32 v[154:155], v[116:117], v[196:197]
	v_pk_fma_f32 v[152:153], v[126:127], v[160:161], v[152:153] neg_lo:[0,0,1] neg_hi:[0,0,1]
	v_pk_mul_f32 v[150:151], v[178:179], v[160:161]
	v_pk_mul_f32 v[160:161], v[116:117], v[148:149]
	v_pk_fma_f32 v[154:155], v[124:125], v[148:149], v[154:155] neg_lo:[0,0,1] neg_hi:[0,0,1]
	v_pk_fma_f32 v[148:149], v[126:127], v[194:195], v[150:151]
	v_pk_fma_f32 v[150:151], v[124:125], v[196:197], v[160:161]
	v_pk_mul_f32 v[194:195], v[114:115], v[146:147]
	v_mov_b32_e32 v196, v175
	v_mov_b32_e32 v197, v177
	v_pk_mul_f32 v[178:179], v[122:123], v[146:147]
	v_pk_mul_f32 v[160:161], v[194:195], v[196:197]
	v_mov_b32_e32 v175, v176
	v_mov_b32_e32 v157, v158
	v_pk_mul_f32 v[162:163], v[112:113], v[198:199]
	v_pk_fma_f32 v[160:161], v[178:179], v[174:175], v[160:161] neg_lo:[0,0,1] neg_hi:[0,0,1]
	v_pk_mul_f32 v[158:159], v[194:195], v[174:175]
	v_pk_mul_f32 v[174:175], v[112:113], v[156:157]
	v_pk_fma_f32 v[162:163], v[120:121], v[156:157], v[162:163] neg_lo:[0,0,1] neg_hi:[0,0,1]
	v_pk_fma_f32 v[156:157], v[178:179], v[196:197], v[158:159]
	v_pk_fma_f32 v[158:159], v[120:121], v[198:199], v[174:175]
	v_mov_b64_e32 v[174:175], s[20:21]
	v_mad_i64_i32 v[174:175], s[10:11], v144, s50, v[174:175]
	v_lshl_add_u64 v[174:175], s[0:1], 1, v[174:175]
	v_lshl_add_u64 v[178:179], v[174:175], 0, v[180:181]
	v_cvt_pk_bf16_f32 v174, v154, v155
	v_cvt_pk_bf16_f32 v175, v152, v153
	v_cvt_pk_bf16_f32 v176, v162, v163
	v_cvt_pk_bf16_f32 v177, v160, v161
	v_cvt_pk_bf16_f32 v150, v150, v151
	v_cvt_pk_bf16_f32 v151, v148, v149
	v_cvt_pk_bf16_f32 v152, v158, v159
	v_cvt_pk_bf16_f32 v153, v156, v157
	global_store_dwordx4 v[178:179], v[174:177], off offset:256
	global_store_dwordx4 v[178:179], v[150:153], off offset:320

.LBB0_851:
	v_mul_f32_e32 v112, 0x3dd53b94, v173
	s_nop 0
	v_or_b32_e32 v114, 16, v144
	v_mov_b32_e32 v113, v112
	v_cndmask_b32_e64 v116, 0, 1, s[34:35]
	v_pk_mul_f32 v[110:111], v[110:111], v[112:113] op_sel_hi:[1,0]
	v_pk_mul_f32 v[108:109], v[108:109], v[112:113] op_sel_hi:[1,0]
	v_ashrrev_i32_e32 v115, 31, v114
	s_mov_b64 s[10:11], -1
	v_cmp_ne_u32_e64 s[42:43], 1, v116
	s_andn2_b64 vcc, exec, s[34:35]
	v_pk_mul_f32 v[100:101], v[100:101], v[112:113]
	v_pk_mul_f32 v[104:105], v[104:105], v[112:113]
	v_pk_mul_f32 v[96:97], v[96:97], v[112:113]
	s_cbranch_vccnz .LBB0_853
	v_lshlrev_b64 v[116:117], 8, v[114:115]
	v_lshl_add_u64 v[120:121], v[138:139], 0, v[116:117]
	v_mov_b32_e32 v113, v112
	v_pk_mul_f32 v[154:155], v[102:103], v[112:113]
	s_waitcnt vmcnt(2)
	v_mov_b32_e32 v124, v206
	v_mov_b32_e32 v125, v207
	v_mov_b32_e32 v126, v208
	v_mov_b32_e32 v127, v209
	v_mov_b32_e32 v150, v210
	v_mov_b32_e32 v151, v211
	v_mov_b32_e32 v152, v212
	v_mov_b32_e32 v153, v213
	v_mov_b32_e32 v116, v214
	v_mov_b32_e32 v117, v215
	v_mov_b32_e32 v118, v216
	v_mov_b32_e32 v119, v217
	v_mov_b32_e32 v146, v220
	v_mov_b32_e32 v147, v221
	v_mov_b32_e32 v148, v222
	v_mov_b32_e32 v149, v223
	v_or_b32_e32 v202, 32, v144
	v_ashrrev_i32_e32 v203, 31, v202
	v_lshlrev_b64 v[202:203], 8, v[202:203]
	v_lshl_add_u64 v[202:203], v[138:139], 0, v[202:203]
	global_load_dwordx4 v[206:209], v[202:203], off offset:32
	global_load_dwordx4 v[210:213], v[202:203], off offset:48
	global_load_dwordx4 v[214:217], v[202:203], off
	global_load_dwordx4 v[220:223], v[202:203], off offset:16
	v_mov_b32_e32 v160, v125
	v_mov_b32_e32 v161, v127
	v_mov_b32_e32 v158, v117
	v_mov_b32_e32 v156, v147
	v_mov_b32_e32 v157, v149
	v_pk_mul_f32 v[120:121], v[154:155], v[156:157]
	v_mov_b32_e32 v159, v119
	v_mov_b32_e32 v147, v148
	v_mov_b32_e32 v117, v118
	v_pk_mul_f32 v[122:123], v[100:101], v[158:159]
	v_pk_fma_f32 v[120:121], v[110:111], v[146:147], v[120:121] neg_lo:[0,0,1] neg_hi:[0,0,1]
	v_pk_mul_f32 v[118:119], v[154:155], v[146:147]
	v_pk_mul_f32 v[146:147], v[100:101], v[116:117]
	v_pk_fma_f32 v[122:123], v[108:109], v[116:117], v[122:123] neg_lo:[0,0,1] neg_hi:[0,0,1]
	v_pk_fma_f32 v[116:117], v[110:111], v[156:157], v[118:119]
	v_pk_fma_f32 v[118:119], v[108:109], v[158:159], v[146:147]
	v_pk_mul_f32 v[156:157], v[98:99], v[112:113]
	v_mov_b32_e32 v158, v151
	v_mov_b32_e32 v159, v153
	v_pk_mul_f32 v[154:155], v[106:107], v[112:113]
	v_pk_mul_f32 v[146:147], v[156:157], v[158:159]
	v_mov_b32_e32 v151, v152
	v_mov_b32_e32 v125, v126
	v_pk_mul_f32 v[148:149], v[96:97], v[160:161]
	v_pk_fma_f32 v[146:147], v[154:155], v[150:151], v[146:147] neg_lo:[0,0,1] neg_hi:[0,0,1]
	v_pk_mul_f32 v[126:127], v[156:157], v[150:151]
	v_pk_mul_f32 v[150:151], v[96:97], v[124:125]
	v_pk_fma_f32 v[148:149], v[104:105], v[124:125], v[148:149] neg_lo:[0,0,1] neg_hi:[0,0,1]
	v_pk_fma_f32 v[124:125], v[154:155], v[158:159], v[126:127]
	v_pk_fma_f32 v[126:127], v[104:105], v[160:161], v[150:151]
	v_mov_b64_e32 v[150:151], s[20:21]
	v_mad_i64_i32 v[150:151], s[10:11], v114, s50, v[150:151]
	v_lshl_add_u64 v[150:151], s[0:1], 1, v[150:151]
	v_lshl_add_u64 v[154:155], v[150:151], 0, v[180:181]
	v_cvt_pk_bf16_f32 v150, v122, v123
	v_cvt_pk_bf16_f32 v151, v120, v121
	v_cvt_pk_bf16_f32 v152, v148, v149
	v_cvt_pk_bf16_f32 v153, v146, v147
	v_cvt_pk_bf16_f32 v118, v118, v119
	v_cvt_pk_bf16_f32 v119, v116, v117
	v_cvt_pk_bf16_f32 v120, v126, v127
	v_cvt_pk_bf16_f32 v121, v124, v125
	s_mov_b64 s[10:11], 0
	global_store_dwordx4 v[154:155], v[150:153], off offset:256
	global_store_dwordx4 v[154:155], v[118:121], off offset:320

.LBB0_855:
	v_mul_f32_e32 v96, 0x3dd53b94, v172
	s_nop 0
	v_or_b32_e32 v98, 32, v144
	v_mov_b32_e32 v97, v96
	v_pk_mul_f32 v[94:95], v[94:95], v[96:97] op_sel_hi:[1,0]
	v_pk_mul_f32 v[92:93], v[92:93], v[96:97] op_sel_hi:[1,0]
	v_ashrrev_i32_e32 v99, 31, v98
	s_mov_b64 s[10:11], -1
	s_and_b64 vcc, exec, s[42:43]
	v_pk_mul_f32 v[84:85], v[84:85], v[96:97]
	v_pk_mul_f32 v[88:89], v[88:89], v[96:97]
	v_pk_mul_f32 v[80:81], v[80:81], v[96:97]
	s_cbranch_vccnz .LBB0_857
	v_lshlrev_b64 v[100:101], 8, v[98:99]
	v_lshl_add_u64 v[104:105], v[138:139], 0, v[100:101]
	v_mov_b32_e32 v97, v96
	v_pk_mul_f32 v[120:121], v[86:87], v[96:97]
	s_waitcnt vmcnt(2)
	v_mov_b32_e32 v108, v206
	v_mov_b32_e32 v109, v207
	v_mov_b32_e32 v110, v208
	v_mov_b32_e32 v111, v209
	v_mov_b32_e32 v116, v210
	v_mov_b32_e32 v117, v211
	v_mov_b32_e32 v118, v212
	v_mov_b32_e32 v119, v213
	v_mov_b32_e32 v100, v214
	v_mov_b32_e32 v101, v215
	v_mov_b32_e32 v102, v216
	v_mov_b32_e32 v103, v217
	v_mov_b32_e32 v112, v220
	v_mov_b32_e32 v113, v221
	v_mov_b32_e32 v114, v222
	v_mov_b32_e32 v115, v223
	v_or_b32_e32 v202, 48, v144
	v_ashrrev_i32_e32 v203, 31, v202
	v_lshlrev_b64 v[202:203], 8, v[202:203]
	v_lshl_add_u64 v[202:203], v[138:139], 0, v[202:203]
	global_load_dwordx4 v[206:209], v[202:203], off offset:32
	global_load_dwordx4 v[210:213], v[202:203], off offset:48
	global_load_dwordx4 v[214:217], v[202:203], off
	global_load_dwordx4 v[220:223], v[202:203], off offset:16
	v_mov_b32_e32 v126, v109
	v_mov_b32_e32 v127, v111
	v_mov_b32_e32 v124, v101
	v_mov_b32_e32 v122, v113
	v_mov_b32_e32 v123, v115
	v_pk_mul_f32 v[104:105], v[120:121], v[122:123]
	v_mov_b32_e32 v125, v103
	v_mov_b32_e32 v113, v114
	v_mov_b32_e32 v101, v102
	v_pk_mul_f32 v[106:107], v[84:85], v[124:125]
	v_pk_fma_f32 v[104:105], v[94:95], v[112:113], v[104:105] neg_lo:[0,0,1] neg_hi:[0,0,1]
	v_pk_mul_f32 v[102:103], v[120:121], v[112:113]
	v_pk_mul_f32 v[112:113], v[84:85], v[100:101]
	v_pk_fma_f32 v[106:107], v[92:93], v[100:101], v[106:107] neg_lo:[0,0,1] neg_hi:[0,0,1]
	v_pk_fma_f32 v[100:101], v[94:95], v[122:123], v[102:103]
	v_pk_fma_f32 v[102:103], v[92:93], v[124:125], v[112:113]
	v_pk_mul_f32 v[122:123], v[82:83], v[96:97]
	v_mov_b32_e32 v124, v117
	v_mov_b32_e32 v125, v119
	v_pk_mul_f32 v[120:121], v[90:91], v[96:97]
	v_pk_mul_f32 v[112:113], v[122:123], v[124:125]
	v_mov_b32_e32 v117, v118
	v_mov_b32_e32 v109, v110
	v_pk_mul_f32 v[114:115], v[80:81], v[126:127]
	v_pk_fma_f32 v[112:113], v[120:121], v[116:117], v[112:113] neg_lo:[0,0,1] neg_hi:[0,0,1]
	v_pk_mul_f32 v[110:111], v[122:123], v[116:117]
	v_pk_mul_f32 v[116:117], v[80:81], v[108:109]
	v_pk_fma_f32 v[114:115], v[88:89], v[108:109], v[114:115] neg_lo:[0,0,1] neg_hi:[0,0,1]
	v_pk_fma_f32 v[108:109], v[120:121], v[124:125], v[110:111]
	v_pk_fma_f32 v[110:111], v[88:89], v[126:127], v[116:117]
	v_mov_b64_e32 v[116:117], s[20:21]
	v_mad_i64_i32 v[116:117], s[10:11], v98, s50, v[116:117]
	v_lshl_add_u64 v[116:117], s[0:1], 1, v[116:117]
	v_lshl_add_u64 v[120:121], v[116:117], 0, v[180:181]
	v_cvt_pk_bf16_f32 v116, v106, v107
	v_cvt_pk_bf16_f32 v117, v104, v105
	v_cvt_pk_bf16_f32 v118, v114, v115
	v_cvt_pk_bf16_f32 v119, v112, v113
	v_cvt_pk_bf16_f32 v102, v102, v103
	v_cvt_pk_bf16_f32 v103, v100, v101
	v_cvt_pk_bf16_f32 v104, v110, v111
	v_cvt_pk_bf16_f32 v105, v108, v109
	s_mov_b64 s[10:11], 0
	global_store_dwordx4 v[120:121], v[116:119], off offset:256
	global_store_dwordx4 v[120:121], v[102:105], off offset:320

.LBB0_859:
	v_mul_f32_e32 v80, 0x3dd53b94, v171
	s_nop 0
	v_or_b32_e32 v82, 48, v144
	v_mov_b32_e32 v81, v80
	v_pk_mul_f32 v[78:79], v[78:79], v[80:81] op_sel_hi:[1,0]
	v_pk_mul_f32 v[76:77], v[76:77], v[80:81] op_sel_hi:[1,0]
	v_ashrrev_i32_e32 v83, 31, v82
	s_mov_b64 s[10:11], -1
	s_and_b64 vcc, exec, s[42:43]
	v_pk_mul_f32 v[68:69], v[68:69], v[80:81]
	v_pk_mul_f32 v[72:73], v[72:73], v[80:81]
	v_pk_mul_f32 v[64:65], v[64:65], v[80:81]
	s_cbranch_vccnz .LBB0_861
	v_lshlrev_b64 v[84:85], 8, v[82:83]
	v_lshl_add_u64 v[88:89], v[138:139], 0, v[84:85]
	v_mov_b32_e32 v81, v80
	v_pk_mul_f32 v[104:105], v[70:71], v[80:81]
	s_waitcnt vmcnt(2)
	v_mov_b32_e32 v92, v206
	v_mov_b32_e32 v93, v207
	v_mov_b32_e32 v94, v208
	v_mov_b32_e32 v95, v209
	v_mov_b32_e32 v100, v210
	v_mov_b32_e32 v101, v211
	v_mov_b32_e32 v102, v212
	v_mov_b32_e32 v103, v213
	v_mov_b32_e32 v84, v214
	v_mov_b32_e32 v85, v215
	v_mov_b32_e32 v86, v216
	v_mov_b32_e32 v87, v217
	v_mov_b32_e32 v96, v220
	v_mov_b32_e32 v97, v221
	v_mov_b32_e32 v98, v222
	v_mov_b32_e32 v99, v223
	v_add_u32_e32 v202, 0x80, v144
	v_ashrrev_i32_e32 v203, 31, v202
	v_lshlrev_b64 v[202:203], 8, v[202:203]
	v_lshl_add_u64 v[202:203], v[138:139], 0, v[202:203]
	global_load_dwordx4 v[206:209], v[202:203], off offset:32
	global_load_dwordx4 v[210:213], v[202:203], off offset:48
	global_load_dwordx4 v[214:217], v[202:203], off
	global_load_dwordx4 v[220:223], v[202:203], off offset:16
	v_mov_b32_e32 v110, v93
	v_mov_b32_e32 v111, v95
	v_mov_b32_e32 v108, v85
	v_mov_b32_e32 v106, v97
	v_mov_b32_e32 v107, v99
	v_pk_mul_f32 v[88:89], v[104:105], v[106:107]
	v_mov_b32_e32 v109, v87
	v_mov_b32_e32 v97, v98
	v_mov_b32_e32 v85, v86
	v_pk_mul_f32 v[90:91], v[68:69], v[108:109]
	v_pk_fma_f32 v[88:89], v[78:79], v[96:97], v[88:89] neg_lo:[0,0,1] neg_hi:[0,0,1]
	v_pk_mul_f32 v[86:87], v[104:105], v[96:97]
	v_pk_mul_f32 v[96:97], v[68:69], v[84:85]
	v_pk_fma_f32 v[90:91], v[76:77], v[84:85], v[90:91] neg_lo:[0,0,1] neg_hi:[0,0,1]
	v_pk_fma_f32 v[84:85], v[78:79], v[106:107], v[86:87]
	v_pk_fma_f32 v[86:87], v[76:77], v[108:109], v[96:97]
	v_pk_mul_f32 v[106:107], v[66:67], v[80:81]
	v_mov_b32_e32 v108, v101
	v_mov_b32_e32 v109, v103
	v_pk_mul_f32 v[104:105], v[74:75], v[80:81]
	v_pk_mul_f32 v[96:97], v[106:107], v[108:109]
	v_mov_b32_e32 v101, v102
	v_mov_b32_e32 v93, v94
	v_pk_mul_f32 v[98:99], v[64:65], v[110:111]
	v_pk_fma_f32 v[96:97], v[104:105], v[100:101], v[96:97] neg_lo:[0,0,1] neg_hi:[0,0,1]
	v_pk_mul_f32 v[94:95], v[106:107], v[100:101]
	v_pk_mul_f32 v[100:101], v[64:65], v[92:93]
	v_pk_fma_f32 v[98:99], v[72:73], v[92:93], v[98:99] neg_lo:[0,0,1] neg_hi:[0,0,1]
	v_pk_fma_f32 v[92:93], v[104:105], v[108:109], v[94:95]
	v_pk_fma_f32 v[94:95], v[72:73], v[110:111], v[100:101]
	v_mov_b64_e32 v[100:101], s[20:21]
	v_mad_i64_i32 v[100:101], s[10:11], v82, s50, v[100:101]
	v_lshl_add_u64 v[100:101], s[0:1], 1, v[100:101]
	v_lshl_add_u64 v[104:105], v[100:101], 0, v[180:181]
	v_cvt_pk_bf16_f32 v100, v90, v91
	v_cvt_pk_bf16_f32 v101, v88, v89
	v_cvt_pk_bf16_f32 v102, v98, v99
	v_cvt_pk_bf16_f32 v103, v96, v97
	v_cvt_pk_bf16_f32 v86, v86, v87
	v_cvt_pk_bf16_f32 v87, v84, v85
	v_cvt_pk_bf16_f32 v88, v94, v95
	v_cvt_pk_bf16_f32 v89, v92, v93
	s_mov_b64 s[10:11], 0
	global_store_dwordx4 v[104:105], v[100:103], off offset:256
	global_store_dwordx4 v[104:105], v[86:89], off offset:320

.LBB0_863:
	v_mul_f32_e32 v64, 0x3dd53b94, v170
	s_nop 0
	v_add_u32_e32 v66, 0x80, v144
	v_mov_b32_e32 v65, v64
	v_pk_mul_f32 v[62:63], v[62:63], v[64:65] op_sel_hi:[1,0]
	v_pk_mul_f32 v[60:61], v[60:61], v[64:65] op_sel_hi:[1,0]
	v_ashrrev_i32_e32 v67, 31, v66
	s_mov_b64 s[10:11], -1
	s_and_b64 vcc, exec, s[42:43]
	v_pk_mul_f32 v[52:53], v[52:53], v[64:65]
	v_pk_mul_f32 v[56:57], v[56:57], v[64:65]
	v_pk_mul_f32 v[48:49], v[48:49], v[64:65]
	s_cbranch_vccnz .LBB0_865
	v_lshlrev_b64 v[68:69], 8, v[66:67]
	v_lshl_add_u64 v[72:73], v[138:139], 0, v[68:69]
	v_mov_b32_e32 v65, v64
	v_pk_mul_f32 v[88:89], v[54:55], v[64:65]
	s_waitcnt vmcnt(2)
	v_mov_b32_e32 v76, v206
	v_mov_b32_e32 v77, v207
	v_mov_b32_e32 v78, v208
	v_mov_b32_e32 v79, v209
	v_mov_b32_e32 v84, v210
	v_mov_b32_e32 v85, v211
	v_mov_b32_e32 v86, v212
	v_mov_b32_e32 v87, v213
	v_mov_b32_e32 v68, v214
	v_mov_b32_e32 v69, v215
	v_mov_b32_e32 v70, v216
	v_mov_b32_e32 v71, v217
	v_mov_b32_e32 v80, v220
	v_mov_b32_e32 v81, v221
	v_mov_b32_e32 v82, v222
	v_mov_b32_e32 v83, v223
	v_add_u32_e32 v202, 0x90, v144
	v_ashrrev_i32_e32 v203, 31, v202
	v_lshlrev_b64 v[202:203], 8, v[202:203]
	v_lshl_add_u64 v[202:203], v[138:139], 0, v[202:203]
	global_load_dwordx4 v[206:209], v[202:203], off offset:32
	global_load_dwordx4 v[210:213], v[202:203], off offset:48
	global_load_dwordx4 v[214:217], v[202:203], off
	global_load_dwordx4 v[220:223], v[202:203], off offset:16
	v_mov_b32_e32 v94, v77
	v_mov_b32_e32 v95, v79
	v_mov_b32_e32 v92, v69
	v_mov_b32_e32 v90, v81
	v_mov_b32_e32 v91, v83
	v_pk_mul_f32 v[72:73], v[88:89], v[90:91]
	v_mov_b32_e32 v93, v71
	v_mov_b32_e32 v81, v82
	v_mov_b32_e32 v69, v70
	v_pk_mul_f32 v[74:75], v[52:53], v[92:93]
	v_pk_fma_f32 v[72:73], v[62:63], v[80:81], v[72:73] neg_lo:[0,0,1] neg_hi:[0,0,1]
	v_pk_mul_f32 v[70:71], v[88:89], v[80:81]
	v_pk_mul_f32 v[80:81], v[52:53], v[68:69]
	v_pk_fma_f32 v[74:75], v[60:61], v[68:69], v[74:75] neg_lo:[0,0,1] neg_hi:[0,0,1]
	v_pk_fma_f32 v[68:69], v[62:63], v[90:91], v[70:71]
	v_pk_fma_f32 v[70:71], v[60:61], v[92:93], v[80:81]
	v_pk_mul_f32 v[90:91], v[50:51], v[64:65]
	v_mov_b32_e32 v92, v85
	v_mov_b32_e32 v93, v87
	v_pk_mul_f32 v[88:89], v[58:59], v[64:65]
	v_pk_mul_f32 v[80:81], v[90:91], v[92:93]
	v_mov_b32_e32 v85, v86
	v_mov_b32_e32 v77, v78
	v_pk_mul_f32 v[82:83], v[48:49], v[94:95]
	v_pk_fma_f32 v[80:81], v[88:89], v[84:85], v[80:81] neg_lo:[0,0,1] neg_hi:[0,0,1]
	v_pk_mul_f32 v[78:79], v[90:91], v[84:85]
	v_pk_mul_f32 v[84:85], v[48:49], v[76:77]
	v_pk_fma_f32 v[82:83], v[56:57], v[76:77], v[82:83] neg_lo:[0,0,1] neg_hi:[0,0,1]
	v_pk_fma_f32 v[76:77], v[88:89], v[92:93], v[78:79]
	v_pk_fma_f32 v[78:79], v[56:57], v[94:95], v[84:85]
	v_mov_b64_e32 v[84:85], s[20:21]
	v_mad_i64_i32 v[84:85], s[10:11], v66, s50, v[84:85]
	v_lshl_add_u64 v[84:85], s[0:1], 1, v[84:85]
	v_lshl_add_u64 v[88:89], v[84:85], 0, v[180:181]
	v_cvt_pk_bf16_f32 v84, v74, v75
	v_cvt_pk_bf16_f32 v85, v72, v73
	v_cvt_pk_bf16_f32 v86, v82, v83
	v_cvt_pk_bf16_f32 v87, v80, v81
	v_cvt_pk_bf16_f32 v70, v70, v71
	v_cvt_pk_bf16_f32 v71, v68, v69
	v_cvt_pk_bf16_f32 v72, v78, v79
	v_cvt_pk_bf16_f32 v73, v76, v77
	s_mov_b64 s[10:11], 0
	global_store_dwordx4 v[88:89], v[84:87], off offset:256
	global_store_dwordx4 v[88:89], v[70:73], off offset:320

.LBB0_867:
	v_mul_f32_e32 v48, 0x3dd53b94, v169
	s_nop 0
	v_add_u32_e32 v50, 0x90, v144
	v_mov_b32_e32 v49, v48
	v_pk_mul_f32 v[46:47], v[46:47], v[48:49] op_sel_hi:[1,0]
	v_pk_mul_f32 v[44:45], v[44:45], v[48:49] op_sel_hi:[1,0]
	v_ashrrev_i32_e32 v51, 31, v50
	s_mov_b64 s[10:11], -1
	s_and_b64 vcc, exec, s[42:43]
	v_pk_mul_f32 v[36:37], v[36:37], v[48:49]
	v_pk_mul_f32 v[40:41], v[40:41], v[48:49]
	v_pk_mul_f32 v[32:33], v[32:33], v[48:49]
	s_cbranch_vccnz .LBB0_869
	v_lshlrev_b64 v[52:53], 8, v[50:51]
	v_lshl_add_u64 v[56:57], v[138:139], 0, v[52:53]
	v_mov_b32_e32 v49, v48
	v_pk_mul_f32 v[72:73], v[38:39], v[48:49]
	s_waitcnt vmcnt(2)
	v_mov_b32_e32 v60, v206
	v_mov_b32_e32 v61, v207
	v_mov_b32_e32 v62, v208
	v_mov_b32_e32 v63, v209
	v_mov_b32_e32 v68, v210
	v_mov_b32_e32 v69, v211
	v_mov_b32_e32 v70, v212
	v_mov_b32_e32 v71, v213
	v_mov_b32_e32 v52, v214
	v_mov_b32_e32 v53, v215
	v_mov_b32_e32 v54, v216
	v_mov_b32_e32 v55, v217
	v_mov_b32_e32 v64, v220
	v_mov_b32_e32 v65, v221
	v_mov_b32_e32 v66, v222
	v_mov_b32_e32 v67, v223
	v_add_u32_e32 v202, 0xa0, v144
	v_ashrrev_i32_e32 v203, 31, v202
	v_lshlrev_b64 v[202:203], 8, v[202:203]
	v_lshl_add_u64 v[202:203], v[138:139], 0, v[202:203]
	global_load_dwordx4 v[206:209], v[202:203], off offset:32
	global_load_dwordx4 v[210:213], v[202:203], off offset:48
	global_load_dwordx4 v[214:217], v[202:203], off
	global_load_dwordx4 v[220:223], v[202:203], off offset:16
	v_mov_b32_e32 v78, v61
	v_mov_b32_e32 v79, v63
	v_mov_b32_e32 v76, v53
	v_mov_b32_e32 v74, v65
	v_mov_b32_e32 v75, v67
	v_pk_mul_f32 v[56:57], v[72:73], v[74:75]
	v_mov_b32_e32 v77, v55
	v_mov_b32_e32 v65, v66
	v_mov_b32_e32 v53, v54
	v_pk_mul_f32 v[58:59], v[36:37], v[76:77]
	v_pk_fma_f32 v[56:57], v[46:47], v[64:65], v[56:57] neg_lo:[0,0,1] neg_hi:[0,0,1]
	v_pk_mul_f32 v[54:55], v[72:73], v[64:65]
	v_pk_mul_f32 v[64:65], v[36:37], v[52:53]
	v_pk_fma_f32 v[58:59], v[44:45], v[52:53], v[58:59] neg_lo:[0,0,1] neg_hi:[0,0,1]
	v_pk_fma_f32 v[52:53], v[46:47], v[74:75], v[54:55]
	v_pk_fma_f32 v[54:55], v[44:45], v[76:77], v[64:65]
	v_pk_mul_f32 v[74:75], v[34:35], v[48:49]
	v_mov_b32_e32 v76, v69
	v_mov_b32_e32 v77, v71
	v_pk_mul_f32 v[72:73], v[42:43], v[48:49]
	v_pk_mul_f32 v[64:65], v[74:75], v[76:77]
	v_mov_b32_e32 v69, v70
	v_mov_b32_e32 v61, v62
	v_pk_mul_f32 v[66:67], v[32:33], v[78:79]
	v_pk_fma_f32 v[64:65], v[72:73], v[68:69], v[64:65] neg_lo:[0,0,1] neg_hi:[0,0,1]
	v_pk_mul_f32 v[62:63], v[74:75], v[68:69]
	v_pk_mul_f32 v[68:69], v[32:33], v[60:61]
	v_pk_fma_f32 v[66:67], v[40:41], v[60:61], v[66:67] neg_lo:[0,0,1] neg_hi:[0,0,1]
	v_pk_fma_f32 v[60:61], v[72:73], v[76:77], v[62:63]
	v_pk_fma_f32 v[62:63], v[40:41], v[78:79], v[68:69]
	v_mov_b64_e32 v[68:69], s[20:21]
	v_mad_i64_i32 v[68:69], s[10:11], v50, s50, v[68:69]
	v_lshl_add_u64 v[68:69], s[0:1], 1, v[68:69]
	v_lshl_add_u64 v[72:73], v[68:69], 0, v[180:181]
	v_cvt_pk_bf16_f32 v68, v58, v59
	v_cvt_pk_bf16_f32 v69, v56, v57
	v_cvt_pk_bf16_f32 v70, v66, v67
	v_cvt_pk_bf16_f32 v71, v64, v65
	v_cvt_pk_bf16_f32 v54, v54, v55
	v_cvt_pk_bf16_f32 v55, v52, v53
	v_cvt_pk_bf16_f32 v56, v62, v63
	v_cvt_pk_bf16_f32 v57, v60, v61
	s_mov_b64 s[10:11], 0
	global_store_dwordx4 v[72:73], v[68:71], off offset:256
	global_store_dwordx4 v[72:73], v[54:57], off offset:320

.LBB0_871:
	s_waitcnt lgkmcnt(1)
	v_mul_f32_e32 v32, 0x3dd53b94, v168
	v_add_u32_e32 v34, 0xa0, v144
	v_mov_b32_e32 v33, v32
	v_pk_mul_f32 v[30:31], v[30:31], v[32:33] op_sel_hi:[1,0]
	v_pk_mul_f32 v[28:29], v[28:29], v[32:33] op_sel_hi:[1,0]
	v_ashrrev_i32_e32 v35, 31, v34
	s_mov_b64 s[10:11], -1
	s_and_b64 vcc, exec, s[42:43]
	v_pk_mul_f32 v[20:21], v[20:21], v[32:33]
	v_pk_mul_f32 v[24:25], v[24:25], v[32:33]
	v_pk_mul_f32 v[16:17], v[16:17], v[32:33]
	s_cbranch_vccnz .LBB0_873
	v_lshlrev_b64 v[36:37], 8, v[34:35]
	v_lshl_add_u64 v[40:41], v[138:139], 0, v[36:37]
	v_mov_b32_e32 v33, v32
	v_pk_mul_f32 v[56:57], v[22:23], v[32:33]
	s_waitcnt vmcnt(2)
	v_mov_b32_e32 v44, v206
	v_mov_b32_e32 v45, v207
	v_mov_b32_e32 v46, v208
	v_mov_b32_e32 v47, v209
	v_mov_b32_e32 v52, v210
	v_mov_b32_e32 v53, v211
	v_mov_b32_e32 v54, v212
	v_mov_b32_e32 v55, v213
	v_mov_b32_e32 v36, v214
	v_mov_b32_e32 v37, v215
	v_mov_b32_e32 v38, v216
	v_mov_b32_e32 v39, v217
	v_mov_b32_e32 v48, v220
	v_mov_b32_e32 v49, v221
	v_mov_b32_e32 v50, v222
	v_mov_b32_e32 v51, v223
	v_add_u32_e32 v202, 0xb0, v144
	v_ashrrev_i32_e32 v203, 31, v202
	v_lshlrev_b64 v[202:203], 8, v[202:203]
	v_lshl_add_u64 v[202:203], v[138:139], 0, v[202:203]
	global_load_dwordx4 v[206:209], v[202:203], off offset:32
	global_load_dwordx4 v[210:213], v[202:203], off offset:48
	global_load_dwordx4 v[214:217], v[202:203], off
	global_load_dwordx4 v[220:223], v[202:203], off offset:16
	v_mov_b32_e32 v62, v45
	v_mov_b32_e32 v63, v47
	v_mov_b32_e32 v60, v37
	v_mov_b32_e32 v58, v49
	v_mov_b32_e32 v59, v51
	v_pk_mul_f32 v[40:41], v[56:57], v[58:59]
	v_mov_b32_e32 v61, v39
	v_mov_b32_e32 v49, v50
	v_mov_b32_e32 v37, v38
	v_pk_mul_f32 v[42:43], v[20:21], v[60:61]
	v_pk_fma_f32 v[40:41], v[30:31], v[48:49], v[40:41] neg_lo:[0,0,1] neg_hi:[0,0,1]
	v_pk_mul_f32 v[38:39], v[56:57], v[48:49]
	v_pk_mul_f32 v[48:49], v[20:21], v[36:37]
	v_pk_fma_f32 v[42:43], v[28:29], v[36:37], v[42:43] neg_lo:[0,0,1] neg_hi:[0,0,1]
	v_pk_fma_f32 v[36:37], v[30:31], v[58:59], v[38:39]
	v_pk_fma_f32 v[38:39], v[28:29], v[60:61], v[48:49]
	v_pk_mul_f32 v[58:59], v[18:19], v[32:33]
	v_mov_b32_e32 v60, v53
	v_mov_b32_e32 v61, v55
	v_pk_mul_f32 v[56:57], v[26:27], v[32:33]
	v_pk_mul_f32 v[48:49], v[58:59], v[60:61]
	v_mov_b32_e32 v53, v54
	v_mov_b32_e32 v45, v46
	v_pk_mul_f32 v[50:51], v[16:17], v[62:63]
	v_pk_fma_f32 v[48:49], v[56:57], v[52:53], v[48:49] neg_lo:[0,0,1] neg_hi:[0,0,1]
	v_pk_mul_f32 v[46:47], v[58:59], v[52:53]
	v_pk_mul_f32 v[52:53], v[16:17], v[44:45]
	v_pk_fma_f32 v[50:51], v[24:25], v[44:45], v[50:51] neg_lo:[0,0,1] neg_hi:[0,0,1]
	v_pk_fma_f32 v[44:45], v[56:57], v[60:61], v[46:47]
	v_pk_fma_f32 v[46:47], v[24:25], v[62:63], v[52:53]
	v_mov_b64_e32 v[52:53], s[20:21]
	v_mad_i64_i32 v[52:53], s[10:11], v34, s50, v[52:53]
	v_lshl_add_u64 v[52:53], s[0:1], 1, v[52:53]
	v_lshl_add_u64 v[56:57], v[52:53], 0, v[180:181]
	v_cvt_pk_bf16_f32 v52, v42, v43
	v_cvt_pk_bf16_f32 v53, v40, v41
	v_cvt_pk_bf16_f32 v54, v50, v51
	v_cvt_pk_bf16_f32 v55, v48, v49
	v_cvt_pk_bf16_f32 v38, v38, v39
	v_cvt_pk_bf16_f32 v39, v36, v37
	v_cvt_pk_bf16_f32 v40, v46, v47
	v_cvt_pk_bf16_f32 v41, v44, v45
	s_mov_b64 s[10:11], 0
	global_store_dwordx4 v[56:57], v[52:55], off offset:256
	global_store_dwordx4 v[56:57], v[38:41], off offset:320

.LBB0_878:
	v_lshlrev_b64 v[20:21], 8, v[18:19]
	v_lshl_add_u64 v[24:25], v[138:139], 0, v[20:21]
	v_mov_b32_e32 v17, v16
	v_pk_mul_f32 v[40:41], v[6:7], v[16:17]
	s_waitcnt vmcnt(2)
	v_mov_b32_e32 v28, v206
	v_mov_b32_e32 v29, v207
	v_mov_b32_e32 v30, v208
	v_mov_b32_e32 v31, v209
	v_mov_b32_e32 v36, v210
	v_mov_b32_e32 v37, v211
	v_mov_b32_e32 v38, v212
	v_mov_b32_e32 v39, v213
	v_mov_b32_e32 v20, v214
	v_mov_b32_e32 v21, v215
	v_mov_b32_e32 v22, v216
	v_mov_b32_e32 v23, v217
	v_mov_b32_e32 v32, v220
	v_mov_b32_e32 v33, v221
	v_mov_b32_e32 v34, v222
	v_mov_b32_e32 v35, v223
	v_mov_b32_e32 v46, v29
	v_mov_b32_e32 v47, v31
	v_mov_b32_e32 v44, v21
	v_mov_b32_e32 v42, v33
	v_mov_b32_e32 v43, v35
	v_pk_mul_f32 v[24:25], v[40:41], v[42:43]
	v_mov_b32_e32 v45, v23
	v_mov_b32_e32 v33, v34
	v_mov_b32_e32 v21, v22
	v_pk_mul_f32 v[26:27], v[4:5], v[44:45]
	v_pk_fma_f32 v[24:25], v[14:15], v[32:33], v[24:25] neg_lo:[0,0,1] neg_hi:[0,0,1]
	v_pk_mul_f32 v[22:23], v[40:41], v[32:33]
	v_pk_mul_f32 v[32:33], v[4:5], v[20:21]
	v_pk_fma_f32 v[26:27], v[12:13], v[20:21], v[26:27] neg_lo:[0,0,1] neg_hi:[0,0,1]
	v_pk_fma_f32 v[20:21], v[14:15], v[42:43], v[22:23]
	v_pk_fma_f32 v[22:23], v[12:13], v[44:45], v[32:33]
	v_pk_mul_f32 v[42:43], v[2:3], v[16:17]
	v_mov_b32_e32 v44, v37
	v_mov_b32_e32 v45, v39
	v_pk_mul_f32 v[40:41], v[10:11], v[16:17]
	v_pk_mul_f32 v[32:33], v[42:43], v[44:45]
	v_mov_b32_e32 v37, v38
	v_mov_b32_e32 v29, v30
	v_pk_mul_f32 v[34:35], v[0:1], v[46:47]
	v_pk_fma_f32 v[32:33], v[40:41], v[36:37], v[32:33] neg_lo:[0,0,1] neg_hi:[0,0,1]
	v_pk_mul_f32 v[30:31], v[42:43], v[36:37]
	v_pk_mul_f32 v[36:37], v[0:1], v[28:29]
	v_pk_fma_f32 v[34:35], v[8:9], v[28:29], v[34:35] neg_lo:[0,0,1] neg_hi:[0,0,1]
	v_pk_fma_f32 v[28:29], v[40:41], v[44:45], v[30:31]
	v_pk_fma_f32 v[30:31], v[8:9], v[46:47], v[36:37]
	v_mov_b64_e32 v[36:37], s[20:21]
	v_mad_i64_i32 v[36:37], s[10:11], v18, s50, v[36:37]
	v_lshl_add_u64 v[36:37], s[0:1], 1, v[36:37]
	v_lshl_add_u64 v[40:41], v[36:37], 0, v[180:181]
	v_cvt_pk_bf16_f32 v36, v26, v27
	v_cvt_pk_bf16_f32 v37, v24, v25
	v_cvt_pk_bf16_f32 v38, v34, v35
	v_cvt_pk_bf16_f32 v39, v32, v33
	v_cvt_pk_bf16_f32 v22, v22, v23
	v_cvt_pk_bf16_f32 v23, v20, v21
	v_cvt_pk_bf16_f32 v24, v30, v31
	v_cvt_pk_bf16_f32 v25, v28, v29
	global_store_dwordx4 v[40:41], v[36:39], off offset:256
	global_store_dwordx4 v[40:41], v[22:25], off offset:320
	s_cbranch_execnz .LBB0_877
